# up GEMM K-loop: LDS-DMA loads in saddr form (SGPR base + 32-bit VGPR offset), drops 16 v_lshl_add_u64 per iteration
# speedup vs baseline: 1.0018x; 1.0018x over previous
; #define PG8_STAGE(bufoff, gbase, voff) do { _Pragma("unroll") for (int _i = 0; _i < 2; ++_i) \
;         __builtin_amdgcn_global_load_lds((const unsigned*)((const char*)(gbase) + (voff)[_i]), (PG8_LAS unsigned*)(lds + (bufoff) + ldsw + _i * 8192), 16, 0, 0); } while (0)
; #define PG8_LDA(dst, b, h) do { _Pragma("unroll") for (int m = 0; m < 4; ++m) _Pragma("unroll") for (int k = 0; k < 2; ++k) dst[m][k] = *(const PG8_LAS bf16x8*)(lds + PG8_SA(b, h) + aoff + m * 2048 + k * 1024); } while (0)
; #define PG8_LDB(dst, b, h) do { _Pragma("unroll") for (int n = 0; n < 2; ++n) _Pragma("unroll") for (int k = 0; k < 2; ++k) dst[n][k] = *(const PG8_LAS bf16x8*)(lds + PG8_SB(b, h) + boff + n * 2048 + k * 1024); } while (0)
; #define PG8_MMA(ai, bj, At, Bt) do { __builtin_amdgcn_s_setprio(1); _Pragma("unroll") for (int m = 0; m < 4; ++m) _Pragma("unroll") for (int n = 0; n < 2; ++n) _Pragma("unroll") for (int k = 0; k < 2; ++k) \
;         acc[ai][bj][m][n] = __builtin_amdgcn_mfma_f32_16x16x32_bf16(Bt[n][k], At[m][k], acc[ai][bj][m][n], 0, 0, 0); __builtin_amdgcn_s_setprio(0); } while (0)
; #define PG8_WAIT_V(n) asm volatile("s_waitcnt vmcnt(" #n ")" ::: "memory")
; #define PG8_WAIT_L(n) asm volatile("s_waitcnt lgkmcnt(" #n ")" ::: "memory")
; #define PG8_BAR __builtin_amdgcn_s_barrier()
; template <class Epi, class Sched, bool ALIGN_EPI = false, bool SP2 = false>
; __device__ __forceinline__ void gemm_phase(PG8_LAS unsigned char* lds, const Gemm g, const Sched& S, const Epi& E, int wid_in) {
;     ...
;             const char* a1 = cA + (size_t)(t + 1) * kstep;
;             const char* a2 = last ? nA : cA + (size_t)(t + 2) * kstep; const char* b2 = last ? nB : cB + (size_t)(t + 2) * kstep;
;             const char* a3 = a2 + kstep; const char* b3 = b2 + kstep;
;             if (last && has_next) S.a_ready(nxt);
;             if constexpr (SP2) {
;             PG8_LDB(B0, 0, 0); PG8_LDB(B1, 0, 1); PG8_SCHED; PG8_LDA(At, 0, 0); PG8_STAGE(PG8_SA(1, 1), a1 + hstep, voffA);
;             PG8_WAIT_V(8); PG8_WAIT_L(0); PG8_BAR; PG8_MMA(0, 0, At, B0); PG8_MMA(0, 1, At, B1); PG8_BAR; PG8_SCHED;
;             PG8_LDA(At, 0, 1); PG8_STAGE(PG8_SB(0, 0), b2, voffB); PG8_STAGE(PG8_SB(0, 1), b2 + hstep, voffB); PG8_STAGE(PG8_SA(0, 0), a2, voffA);
;             PG8_WAIT_V(8); PG8_WAIT_L(0); PG8_BAR; PG8_MMA(1, 0, At, B0); PG8_MMA(1, 1, At, B1); PG8_BAR; PG8_SCHED;
.LBB0_1153:
	s_add_u32 s26, s24, 0xfff80080
	s_addc_u32 s27, s25, -1
	s_add_i32 s40, 0, 0x10000
	s_cmp_eq_u32 s73, 28
	s_cselect_b32 s29, s19, s27
	s_cselect_b32 s28, s64, s26
	v_add_u32_e32 v140, s40, v142
	s_cselect_b32 s27, s17, s63
	s_cselect_b32 s26, s65, s72
	s_add_i32 s42, 0, 0x14000
	ds_read_b128 v[144:147], v140
	ds_read_b128 v[148:151], v140 offset:1024
	ds_read_b128 v[152:155], v140 offset:2048
	ds_read_b128 v[156:159], v140 offset:3072
	v_add_u32_e32 v140, s42, v142
	ds_read_b128 v[160:163], v140
	ds_read_b128 v[164:167], v140 offset:1024
	ds_read_b128 v[168:171], v140 offset:2048
	ds_read_b128 v[172:175], v140 offset:3072
	s_add_i32 m0, s34, 0xc000
	ds_read_b128 v[176:179], v143
	ds_read_b128 v[180:183], v143 offset:1024
	ds_read_b128 v[184:187], v143 offset:2048
	ds_read_b128 v[188:191], v143 offset:3072
	ds_read_b128 v[208:211], v143 offset:4096
	ds_read_b128 v[212:215], v143 offset:5120
	ds_read_b128 v[216:219], v143 offset:6144
	ds_read_b128 v[220:223], v143 offset:7168
	global_load_lds_dwordx4 v138, s[24:25]
	s_add_i32 m0, s34, 0xe000
	s_nop 0
	global_load_lds_dwordx4 v136, s[24:25]
	s_waitcnt vmcnt(8)
	s_waitcnt lgkmcnt(0)
	s_barrier
	s_setprio 1
	s_waitcnt lgkmcnt(0)
	v_mfma_f32_16x16x32_bf16 v[126:129], v[144:147], v[176:179], v[126:129]
	v_mfma_f32_16x16x32_bf16 v[122:125], v[152:155], v[176:179], v[122:125]
	v_mfma_f32_16x16x32_bf16 v[110:113], v[144:147], v[184:187], v[110:113]
	v_mfma_f32_16x16x32_bf16 v[106:109], v[152:155], v[184:187], v[106:109]
	v_mfma_f32_16x16x32_bf16 v[94:97], v[144:147], v[208:211], v[94:97]
	v_mfma_f32_16x16x32_bf16 v[90:93], v[152:155], v[208:211], v[90:93]
	v_mfma_f32_16x16x32_bf16 v[78:81], v[144:147], v[216:219], v[78:81]
	v_mfma_f32_16x16x32_bf16 v[74:77], v[152:155], v[216:219], v[74:77]
	v_mfma_f32_16x16x32_bf16 v[126:129], v[148:151], v[180:183], v[126:129]
	v_mfma_f32_16x16x32_bf16 v[122:125], v[156:159], v[180:183], v[122:125]
	v_mfma_f32_16x16x32_bf16 v[110:113], v[148:151], v[188:191], v[110:113]
	v_mfma_f32_16x16x32_bf16 v[106:109], v[156:159], v[188:191], v[106:109]
	v_mfma_f32_16x16x32_bf16 v[94:97], v[148:151], v[212:215], v[94:97]
	v_mfma_f32_16x16x32_bf16 v[90:93], v[156:159], v[212:215], v[90:93]
	v_mfma_f32_16x16x32_bf16 v[78:81], v[148:151], v[220:223], v[78:81]
	v_mfma_f32_16x16x32_bf16 v[74:77], v[156:159], v[220:223], v[74:77]
	s_setprio 0
	s_setprio 1
	v_mfma_f32_16x16x32_bf16 v[118:121], v[160:163], v[176:179], v[118:121]
	v_mfma_f32_16x16x32_bf16 v[114:117], v[168:171], v[176:179], v[114:117]
	v_mfma_f32_16x16x32_bf16 v[102:105], v[160:163], v[184:187], v[102:105]
	v_mfma_f32_16x16x32_bf16 v[98:101], v[168:171], v[184:187], v[98:101]
	v_mfma_f32_16x16x32_bf16 v[86:89], v[160:163], v[208:211], v[86:89]
	v_mfma_f32_16x16x32_bf16 v[82:85], v[168:171], v[208:211], v[82:85]
	v_mfma_f32_16x16x32_bf16 v[70:73], v[160:163], v[216:219], v[70:73]
	v_mfma_f32_16x16x32_bf16 v[66:69], v[168:171], v[216:219], v[66:69]
	v_mfma_f32_16x16x32_bf16 v[118:121], v[164:167], v[180:183], v[118:121]
	v_mfma_f32_16x16x32_bf16 v[114:117], v[172:175], v[180:183], v[114:117]
	v_mfma_f32_16x16x32_bf16 v[102:105], v[164:167], v[188:191], v[102:105]
	v_mfma_f32_16x16x32_bf16 v[98:101], v[172:175], v[188:191], v[98:101]
	v_mfma_f32_16x16x32_bf16 v[86:89], v[164:167], v[212:215], v[86:89]
	v_mfma_f32_16x16x32_bf16 v[82:85], v[172:175], v[212:215], v[82:85]
	v_mfma_f32_16x16x32_bf16 v[70:73], v[164:167], v[220:223], v[70:73]
	v_mfma_f32_16x16x32_bf16 v[66:69], v[172:175], v[220:223], v[66:69]
	s_setprio 0
	s_barrier
	s_add_i32 s40, s40, s59
	s_add_u32 s98, s26, 0x80
	s_addc_u32 s99, s27, 0
	s_add_u32 s100, s28, 0x80
	s_addc_u32 s101, s29, 0
	s_mov_b32 m0, s40
	ds_read_b128 v[176:179], v143 offset:16384
	ds_read_b128 v[180:183], v143 offset:17408
	ds_read_b128 v[184:187], v143 offset:18432
	ds_read_b128 v[188:191], v143 offset:19456
	ds_read_b128 v[208:211], v143 offset:20480
	ds_read_b128 v[212:215], v143 offset:21504
	ds_read_b128 v[216:219], v143 offset:22528
	ds_read_b128 v[220:223], v143 offset:23552
	global_load_lds_dwordx4 v0, s[26:27]
	s_add_i32 m0, s40, 0x2000
	s_add_u32 s40, s26, 0x80000
	s_addc_u32 s41, s27, 0
	s_add_i32 s42, s42, s59
	global_load_lds_dwordx4 v130, s[26:27]
	s_mov_b32 m0, s42
	s_nop 0
	global_load_lds_dwordx4 v0, s[40:41]
	s_add_i32 m0, s42, 0x2000
	s_nop 0
	global_load_lds_dwordx4 v130, s[40:41]
	s_mov_b32 m0, s34
	s_nop 0
	global_load_lds_dwordx4 v134, s[28:29]
	s_mov_b32 m0, s35
	s_nop 0
	global_load_lds_dwordx4 v132, s[28:29]
	s_waitcnt vmcnt(8)
	s_waitcnt lgkmcnt(0)
	s_barrier
; #define PG8_STAGE(bufoff, gbase, voff) do { _Pragma("unroll") for (int _i = 0; _i < 2; ++_i) \
;         __builtin_amdgcn_global_load_lds((const unsigned*)((const char*)(gbase) + (voff)[_i]), (PG8_LAS unsigned*)(lds + (bufoff) + ldsw + _i * 8192), 16, 0, 0); } while (0)
; #define PG8_LDA(dst, b, h) do { _Pragma("unroll") for (int m = 0; m < 4; ++m) _Pragma("unroll") for (int k = 0; k < 2; ++k) dst[m][k] = *(const PG8_LAS bf16x8*)(lds + PG8_SA(b, h) + aoff + m * 2048 + k * 1024); } while (0)
; #define PG8_LDB(dst, b, h) do { _Pragma("unroll") for (int n = 0; n < 2; ++n) _Pragma("unroll") for (int k = 0; k < 2; ++k) dst[n][k] = *(const PG8_LAS bf16x8*)(lds + PG8_SB(b, h) + boff + n * 2048 + k * 1024); } while (0)
; #define PG8_MMA(ai, bj, At, Bt) do { __builtin_amdgcn_s_setprio(1); _Pragma("unroll") for (int m = 0; m < 4; ++m) _Pragma("unroll") for (int n = 0; n < 2; ++n) _Pragma("unroll") for (int k = 0; k < 2; ++k) \
;         acc[ai][bj][m][n] = __builtin_amdgcn_mfma_f32_16x16x32_bf16(Bt[n][k], At[m][k], acc[ai][bj][m][n], 0, 0, 0); __builtin_amdgcn_s_setprio(0); } while (0)
; #define PG8_WAIT_V(n) asm volatile("s_waitcnt vmcnt(" #n ")" ::: "memory")
; #define PG8_WAIT_L(n) asm volatile("s_waitcnt lgkmcnt(" #n ")" ::: "memory")
; #define PG8_BAR __builtin_amdgcn_s_barrier()
; #define PG8_SCHED __builtin_amdgcn_sched_barrier(0)
; template <class Epi, class Sched, bool ALIGN_EPI = false, bool SP2 = false>
; __device__ __forceinline__ void gemm_phase(PG8_LAS unsigned char* lds, const Gemm g, const Sched& S, const Epi& E, int wid_in) {
;     ...
;             PG8_WAIT_V(8); PG8_WAIT_L(0); PG8_BAR; PG8_MMA(1, 0, At, B0); PG8_MMA(1, 1, At, B1); PG8_BAR; PG8_SCHED;
;             PG8_LDB(B0, 1, 0); PG8_LDB(B1, 1, 1); PG8_SCHED; PG8_LDA(At, 1, 0); PG8_STAGE(PG8_SA(0, 1), a2 + hstep, voffA);
;             PG8_WAIT_V(8); PG8_WAIT_L(0); PG8_BAR; PG8_MMA(0, 0, At, B0); PG8_MMA(0, 1, At, B1); PG8_BAR; PG8_SCHED;
	s_setprio 1
	s_waitcnt lgkmcnt(0)
	v_mfma_f32_16x16x32_bf16 v[62:65], v[144:147], v[176:179], v[62:65]
	v_mfma_f32_16x16x32_bf16 v[58:61], v[152:155], v[176:179], v[58:61]
	v_mfma_f32_16x16x32_bf16 v[46:49], v[144:147], v[184:187], v[46:49]
	v_mfma_f32_16x16x32_bf16 v[42:45], v[152:155], v[184:187], v[42:45]
	v_mfma_f32_16x16x32_bf16 v[30:33], v[144:147], v[208:211], v[30:33]
	v_mfma_f32_16x16x32_bf16 v[26:29], v[152:155], v[208:211], v[26:29]
	v_mfma_f32_16x16x32_bf16 v[14:17], v[144:147], v[216:219], v[14:17]
	v_mfma_f32_16x16x32_bf16 v[10:13], v[152:155], v[216:219], v[10:13]
	v_mfma_f32_16x16x32_bf16 v[62:65], v[148:151], v[180:183], v[62:65]
	v_mfma_f32_16x16x32_bf16 v[58:61], v[156:159], v[180:183], v[58:61]
	v_mfma_f32_16x16x32_bf16 v[46:49], v[148:151], v[188:191], v[46:49]
	v_mfma_f32_16x16x32_bf16 v[42:45], v[156:159], v[188:191], v[42:45]
	v_mfma_f32_16x16x32_bf16 v[30:33], v[148:151], v[212:215], v[30:33]
	v_mfma_f32_16x16x32_bf16 v[26:29], v[156:159], v[212:215], v[26:29]
	v_mfma_f32_16x16x32_bf16 v[14:17], v[148:151], v[220:223], v[14:17]
	v_mfma_f32_16x16x32_bf16 v[10:13], v[156:159], v[220:223], v[10:13]
	s_setprio 0
	s_setprio 1
	v_mfma_f32_16x16x32_bf16 v[54:57], v[160:163], v[176:179], v[54:57]
	v_mfma_f32_16x16x32_bf16 v[50:53], v[168:171], v[176:179], v[50:53]
	v_mfma_f32_16x16x32_bf16 v[38:41], v[160:163], v[184:187], v[38:41]
	v_mfma_f32_16x16x32_bf16 v[34:37], v[168:171], v[184:187], v[34:37]
	v_mfma_f32_16x16x32_bf16 v[22:25], v[160:163], v[208:211], v[22:25]
	v_mfma_f32_16x16x32_bf16 v[18:21], v[168:171], v[208:211], v[18:21]
	v_mfma_f32_16x16x32_bf16 v[6:9], v[160:163], v[216:219], v[6:9]
	v_mfma_f32_16x16x32_bf16 v[2:5], v[168:171], v[216:219], v[2:5]
	v_mfma_f32_16x16x32_bf16 v[54:57], v[164:167], v[180:183], v[54:57]
	v_mfma_f32_16x16x32_bf16 v[50:53], v[172:175], v[180:183], v[50:53]
	v_mfma_f32_16x16x32_bf16 v[38:41], v[164:167], v[188:191], v[38:41]
	v_mfma_f32_16x16x32_bf16 v[34:37], v[172:175], v[188:191], v[34:37]
	v_mfma_f32_16x16x32_bf16 v[22:25], v[164:167], v[212:215], v[22:25]
	v_mfma_f32_16x16x32_bf16 v[18:21], v[172:175], v[212:215], v[18:21]
	v_mfma_f32_16x16x32_bf16 v[6:9], v[164:167], v[220:223], v[6:9]
	v_mfma_f32_16x16x32_bf16 v[2:5], v[172:175], v[220:223], v[2:5]
	s_setprio 0
	s_barrier
	s_add_i32 s40, 0, 0x18000
	s_add_i32 s41, 0, 0x1c000
	v_add_u32_e32 v156, s40, v142
	v_add_u32_e32 v172, s41, v142
	ds_read_b128 v[144:147], v156
	ds_read_b128 v[148:151], v156 offset:1024
	ds_read_b128 v[152:155], v156 offset:2048
	ds_read_b128 v[156:159], v156 offset:3072
	ds_read_b128 v[160:163], v172
	ds_read_b128 v[164:167], v172 offset:1024
	ds_read_b128 v[168:171], v172 offset:2048
	ds_read_b128 v[172:175], v172 offset:3072
	s_add_u32 s28, s28, 0x80000
	s_addc_u32 s29, s29, 0
	s_mov_b32 m0, s36
	ds_read_b128 v[176:179], v143 offset:32768
	ds_read_b128 v[180:183], v143 offset:33792
	ds_read_b128 v[184:187], v143 offset:34816
	ds_read_b128 v[188:191], v143 offset:35840
	ds_read_b128 v[208:211], v143 offset:36864
	ds_read_b128 v[212:215], v143 offset:37888
	ds_read_b128 v[216:219], v143 offset:38912
	ds_read_b128 v[220:223], v143 offset:39936
	global_load_lds_dwordx4 v134, s[28:29]
	s_mov_b32 m0, s37
	s_nop 0
	global_load_lds_dwordx4 v132, s[28:29]
	s_waitcnt vmcnt(8)
	s_waitcnt lgkmcnt(0)
	s_barrier
	s_setprio 1
	s_waitcnt lgkmcnt(0)
	v_mfma_f32_16x16x32_bf16 v[126:129], v[144:147], v[176:179], v[126:129]
	v_mfma_f32_16x16x32_bf16 v[122:125], v[152:155], v[176:179], v[122:125]
	v_mfma_f32_16x16x32_bf16 v[110:113], v[144:147], v[184:187], v[110:113]
	v_mfma_f32_16x16x32_bf16 v[106:109], v[152:155], v[184:187], v[106:109]
	v_mfma_f32_16x16x32_bf16 v[94:97], v[144:147], v[208:211], v[94:97]
	v_mfma_f32_16x16x32_bf16 v[90:93], v[152:155], v[208:211], v[90:93]
	v_mfma_f32_16x16x32_bf16 v[78:81], v[144:147], v[216:219], v[78:81]
	v_mfma_f32_16x16x32_bf16 v[74:77], v[152:155], v[216:219], v[74:77]
	v_mfma_f32_16x16x32_bf16 v[126:129], v[148:151], v[180:183], v[126:129]
	v_mfma_f32_16x16x32_bf16 v[122:125], v[156:159], v[180:183], v[122:125]
	v_mfma_f32_16x16x32_bf16 v[110:113], v[148:151], v[188:191], v[110:113]
	v_mfma_f32_16x16x32_bf16 v[106:109], v[156:159], v[188:191], v[106:109]
	v_mfma_f32_16x16x32_bf16 v[94:97], v[148:151], v[212:215], v[94:97]
	v_mfma_f32_16x16x32_bf16 v[90:93], v[156:159], v[212:215], v[90:93]
	v_mfma_f32_16x16x32_bf16 v[78:81], v[148:151], v[220:223], v[78:81]
	v_mfma_f32_16x16x32_bf16 v[74:77], v[156:159], v[220:223], v[74:77]
	s_setprio 0
	s_setprio 1
	v_mfma_f32_16x16x32_bf16 v[118:121], v[160:163], v[176:179], v[118:121]
	v_mfma_f32_16x16x32_bf16 v[114:117], v[168:171], v[176:179], v[114:117]
	v_mfma_f32_16x16x32_bf16 v[102:105], v[160:163], v[184:187], v[102:105]
	v_mfma_f32_16x16x32_bf16 v[98:101], v[168:171], v[184:187], v[98:101]
	v_mfma_f32_16x16x32_bf16 v[86:89], v[160:163], v[208:211], v[86:89]
	v_mfma_f32_16x16x32_bf16 v[82:85], v[168:171], v[208:211], v[82:85]
	v_mfma_f32_16x16x32_bf16 v[70:73], v[160:163], v[216:219], v[70:73]
	v_mfma_f32_16x16x32_bf16 v[66:69], v[168:171], v[216:219], v[66:69]
	v_mfma_f32_16x16x32_bf16 v[118:121], v[164:167], v[180:183], v[118:121]
	v_mfma_f32_16x16x32_bf16 v[114:117], v[172:175], v[180:183], v[114:117]
	v_mfma_f32_16x16x32_bf16 v[102:105], v[164:167], v[188:191], v[102:105]
	v_mfma_f32_16x16x32_bf16 v[98:101], v[172:175], v[188:191], v[98:101]
	v_mfma_f32_16x16x32_bf16 v[86:89], v[164:167], v[212:215], v[86:89]
	v_mfma_f32_16x16x32_bf16 v[82:85], v[172:175], v[212:215], v[82:85]
	v_mfma_f32_16x16x32_bf16 v[70:73], v[164:167], v[220:223], v[70:73]
	v_mfma_f32_16x16x32_bf16 v[66:69], v[172:175], v[220:223], v[66:69]
	s_setprio 0
	s_barrier
; #define PG8_STAGE(bufoff, gbase, voff) do { _Pragma("unroll") for (int _i = 0; _i < 2; ++_i) \
;         __builtin_amdgcn_global_load_lds((const unsigned*)((const char*)(gbase) + (voff)[_i]), (PG8_LAS unsigned*)(lds + (bufoff) + ldsw + _i * 8192), 16, 0, 0); } while (0)
; #define PG8_LDA(dst, b, h) do { _Pragma("unroll") for (int m = 0; m < 4; ++m) _Pragma("unroll") for (int k = 0; k < 2; ++k) dst[m][k] = *(const PG8_LAS bf16x8*)(lds + PG8_SA(b, h) + aoff + m * 2048 + k * 1024); } while (0)
; #define PG8_WAIT_V(n) asm volatile("s_waitcnt vmcnt(" #n ")" ::: "memory")
; #define PG8_WAIT_L(n) asm volatile("s_waitcnt lgkmcnt(" #n ")" ::: "memory")
; #define PG8_BAR __builtin_amdgcn_s_barrier()
; template <class Epi, class Sched, bool ALIGN_EPI = false, bool SP2 = false>
; __device__ __forceinline__ void gemm_phase(PG8_LAS unsigned char* lds, const Gemm g, const Sched& S, const Epi& E, int wid_in) {
;     ...
;         for (int t = 0; t < nt; t += 2) {
;             const bool last = (t == nt - 2);
;             const char* a1 = cA + (size_t)(t + 1) * kstep;
;             const char* a2 = last ? nA : cA + (size_t)(t + 2) * kstep; const char* b2 = last ? nB : cB + (size_t)(t + 2) * kstep;
;             const char* a3 = a2 + kstep; const char* b3 = b2 + kstep;
;             if (last && has_next) S.a_ready(nxt);
;             if constexpr (SP2) {
;             PG8_LDB(B0, 0, 0); PG8_LDB(B1, 0, 1); PG8_SCHED; PG8_LDA(At, 0, 0); PG8_STAGE(PG8_SA(1, 1), a1 + hstep, voffA);
;             PG8_WAIT_V(8); PG8_WAIT_L(0); PG8_BAR; PG8_MMA(0, 0, At, B0); PG8_MMA(0, 1, At, B1); PG8_BAR; PG8_SCHED;
;             PG8_LDA(At, 0, 1); PG8_STAGE(PG8_SB(0, 0), b2, voffB); PG8_STAGE(PG8_SB(0, 1), b2 + hstep, voffB); PG8_STAGE(PG8_SA(0, 0), a2, voffA);
;             PG8_WAIT_V(8); PG8_WAIT_L(0); PG8_BAR; PG8_MMA(1, 0, At, B0); PG8_MMA(1, 1, At, B1); PG8_BAR; PG8_SCHED;
;             PG8_LDB(B0, 1, 0); PG8_LDB(B1, 1, 1); PG8_SCHED; PG8_LDA(At, 1, 0); PG8_STAGE(PG8_SA(0, 1), a2 + hstep, voffA);
;             PG8_WAIT_V(8); PG8_WAIT_L(0); PG8_BAR; PG8_MMA(0, 0, At, B0); PG8_MMA(0, 1, At, B1); PG8_BAR; PG8_SCHED;
;             PG8_LDA(At, 1, 1); PG8_STAGE(PG8_SB(1, 0), b3, voffB); PG8_STAGE(PG8_SB(1, 1), b3 + hstep, voffB); PG8_STAGE(PG8_SA(1, 0), a3, voffA);
;             PG8_WAIT_V(8); PG8_WAIT_L(0); PG8_BAR; PG8_MMA(1, 0, At, B0); PG8_MMA(1, 1, At, B1); PG8_BAR; PG8_SCHED;
	s_add_i32 s28, s40, s59
	s_mov_b32 m0, s28
	ds_read_b128 v[176:179], v143 offset:49152
	ds_read_b128 v[180:183], v143 offset:50176
	ds_read_b128 v[184:187], v143 offset:51200
	ds_read_b128 v[188:191], v143 offset:52224
	ds_read_b128 v[208:211], v143 offset:53248
	ds_read_b128 v[212:215], v143 offset:54272
	ds_read_b128 v[216:219], v143 offset:55296
	ds_read_b128 v[220:223], v143 offset:56320
	global_load_lds_dwordx4 v0, s[98:99]
	s_add_i32 m0, s28, 0x2000
	s_add_u32 s26, s26, 0x80080
	s_addc_u32 s27, s27, 0
	s_add_i32 s28, s41, s59
	global_load_lds_dwordx4 v130, s[98:99]
	s_mov_b32 m0, s28
	s_nop 0
	global_load_lds_dwordx4 v0, s[26:27]
	s_add_i32 m0, s28, 0x2000
	s_nop 0
	global_load_lds_dwordx4 v130, s[26:27]
	s_mov_b32 m0, s48
	s_nop 0
	global_load_lds_dwordx4 v134, s[100:101]
	s_mov_b32 m0, s52
	s_nop 0
	global_load_lds_dwordx4 v132, s[100:101]
	s_waitcnt vmcnt(8)
	s_waitcnt lgkmcnt(0)
	s_barrier
	s_setprio 1
	s_waitcnt lgkmcnt(0)
	v_mfma_f32_16x16x32_bf16 v[62:65], v[144:147], v[176:179], v[62:65]
	v_mfma_f32_16x16x32_bf16 v[58:61], v[152:155], v[176:179], v[58:61]
	v_mfma_f32_16x16x32_bf16 v[46:49], v[144:147], v[184:187], v[46:49]
	v_mfma_f32_16x16x32_bf16 v[42:45], v[152:155], v[184:187], v[42:45]
	v_mfma_f32_16x16x32_bf16 v[30:33], v[144:147], v[208:211], v[30:33]
	v_mfma_f32_16x16x32_bf16 v[26:29], v[152:155], v[208:211], v[26:29]
	v_mfma_f32_16x16x32_bf16 v[14:17], v[144:147], v[216:219], v[14:17]
	v_mfma_f32_16x16x32_bf16 v[10:13], v[152:155], v[216:219], v[10:13]
	v_mfma_f32_16x16x32_bf16 v[62:65], v[148:151], v[180:183], v[62:65]
	v_mfma_f32_16x16x32_bf16 v[58:61], v[156:159], v[180:183], v[58:61]
	v_mfma_f32_16x16x32_bf16 v[46:49], v[148:151], v[188:191], v[46:49]
	v_mfma_f32_16x16x32_bf16 v[42:45], v[156:159], v[188:191], v[42:45]
	v_mfma_f32_16x16x32_bf16 v[30:33], v[148:151], v[212:215], v[30:33]
	v_mfma_f32_16x16x32_bf16 v[26:29], v[156:159], v[212:215], v[26:29]
	v_mfma_f32_16x16x32_bf16 v[14:17], v[148:151], v[220:223], v[14:17]
	v_mfma_f32_16x16x32_bf16 v[10:13], v[156:159], v[220:223], v[10:13]
	s_setprio 0
	s_setprio 1
	v_mfma_f32_16x16x32_bf16 v[54:57], v[160:163], v[176:179], v[54:57]
	v_mfma_f32_16x16x32_bf16 v[50:53], v[168:171], v[176:179], v[50:53]
	v_mfma_f32_16x16x32_bf16 v[38:41], v[160:163], v[184:187], v[38:41]
	v_mfma_f32_16x16x32_bf16 v[34:37], v[168:171], v[184:187], v[34:37]
	v_mfma_f32_16x16x32_bf16 v[22:25], v[160:163], v[208:211], v[22:25]
	v_mfma_f32_16x16x32_bf16 v[18:21], v[168:171], v[208:211], v[18:21]
	v_mfma_f32_16x16x32_bf16 v[6:9], v[160:163], v[216:219], v[6:9]
	v_mfma_f32_16x16x32_bf16 v[2:5], v[168:171], v[216:219], v[2:5]
	v_mfma_f32_16x16x32_bf16 v[54:57], v[164:167], v[180:183], v[54:57]
	v_mfma_f32_16x16x32_bf16 v[50:53], v[172:175], v[180:183], v[50:53]
	v_mfma_f32_16x16x32_bf16 v[38:41], v[164:167], v[188:191], v[38:41]
	v_mfma_f32_16x16x32_bf16 v[34:37], v[172:175], v[188:191], v[34:37]
	v_mfma_f32_16x16x32_bf16 v[22:25], v[164:167], v[212:215], v[22:25]
	v_mfma_f32_16x16x32_bf16 v[18:21], v[172:175], v[212:215], v[18:21]
	v_mfma_f32_16x16x32_bf16 v[6:9], v[164:167], v[220:223], v[6:9]
	v_mfma_f32_16x16x32_bf16 v[2:5], v[172:175], v[220:223], v[2:5]
	s_setprio 0
	s_barrier
	s_add_i32 s73, s73, 2
	s_add_u32 s72, s72, 0x100
	s_addc_u32 s63, s63, 0
	s_add_u32 s24, s24, 0x100
	s_addc_u32 s25, s25, 0
	s_cmp_gt_u32 s73, 29
	s_cbranch_scc0 .LBB0_1153
	s_and_b64 vcc, exec, s[14:15]
	s_cbranch_vccz .LBB0_1156
	s_barrier

; #define LAS __attribute__((address_space(3)))
; __device__ __forceinline__ int launder_si(int v) { asm volatile("" : "+s"(v)); return v; }
; __global__ void __launch_bounds__(NWAVES * 64, 2) trunk_fwd(Args args) {
;     extern __shared__ __attribute__((aligned(16))) unsigned char lds[];
;     Frame F;
;     F.lds = (LAS unsigned char*)lds;
;     F.wave = __builtin_amdgcn_readfirstlane((int)threadIdx.x >> 6);
;     F.G = gridDim.x; { const int bx = blockIdx.x; F.vcu = launder_si((F.G % 8 == 0) ? (bx % 8) * (F.G / 8) + bx / 8 : bx); }
;     F.out = args.out; F.ws = args.ws;
;     volatile LAS unsigned* MISC = (volatile LAS unsigned*)(F.lds + MISC_OFF);
;     for (int u = threadIdx.x; u < (LDS_BYTES - LDSCTL_OFF) / 4; u += NWAVES * 64) ((LAS unsigned*)(F.lds + LDSCTL_OFF))[u] = 0u;
;     __syncthreads();
	.amdhsa_kernel _Z9trunk_fwd4Args
		.amdhsa_group_segment_fixed_size 0
		.amdhsa_private_segment_fixed_size 0
		.amdhsa_kernarg_size 488
		.amdhsa_user_sgpr_count 2
		.amdhsa_user_sgpr_dispatch_ptr 0
		.amdhsa_user_sgpr_queue_ptr 0
		.amdhsa_user_sgpr_kernarg_segment_ptr 1
		.amdhsa_user_sgpr_dispatch_id 0
		.amdhsa_user_sgpr_kernarg_preload_length 0
		.amdhsa_user_sgpr_kernarg_preload_offset 0
		.amdhsa_user_sgpr_private_segment_size 0
		.amdhsa_uses_dynamic_stack 0
		.amdhsa_enable_private_segment 0
		.amdhsa_system_sgpr_workgroup_id_x 1
		.amdhsa_system_sgpr_workgroup_id_y 0
		.amdhsa_system_sgpr_workgroup_id_z 0
		.amdhsa_system_sgpr_workgroup_info 0
		.amdhsa_system_vgpr_workitem_id 0
		.amdhsa_next_free_vgpr 256
		.amdhsa_next_free_sgpr 102
		.amdhsa_accum_offset 256
		.amdhsa_reserve_vcc 1
		.amdhsa_float_round_mode_32 0
		.amdhsa_float_round_mode_16_64 0
		.amdhsa_float_denorm_mode_32 3
		.amdhsa_float_denorm_mode_16_64 3
		.amdhsa_dx10_clamp 1
		.amdhsa_ieee_mode 1
		.amdhsa_fp16_overflow 0
		.amdhsa_tg_split 0
		.amdhsa_exception_fp_ieee_invalid_op 0
		.amdhsa_exception_fp_denorm_src 0
		.amdhsa_exception_fp_ieee_div_zero 0
		.amdhsa_exception_fp_ieee_overflow 0
		.amdhsa_exception_fp_ieee_underflow 0
		.amdhsa_exception_fp_ieee_inexact 0
		.amdhsa_exception_int_div_zero 0
	.end_amdhsa_kernel

; __global__ void __launch_bounds__(NWAVES * 64, 2) trunk_fwd(Args args) {
amdhsa.kernels:
  - .agpr_count:     0
    .args:
      - .offset:         0
        .size:           232
        .value_kind:     by_value
      - .offset:         232
        .size:           4
        .value_kind:     hidden_block_count_x
      - .offset:         236
        .size:           4
        .value_kind:     hidden_block_count_y
      - .offset:         240
        .size:           4
        .value_kind:     hidden_block_count_z
      - .offset:         244
        .size:           2
        .value_kind:     hidden_group_size_x
      - .offset:         246
        .size:           2
        .value_kind:     hidden_group_size_y
      - .offset:         248
        .size:           2
        .value_kind:     hidden_group_size_z
      - .offset:         250
        .size:           2
        .value_kind:     hidden_remainder_x
      - .offset:         252
        .size:           2
        .value_kind:     hidden_remainder_y
      - .offset:         254
        .size:           2
        .value_kind:     hidden_remainder_z
      - .offset:         272
        .size:           8
        .value_kind:     hidden_global_offset_x
      - .offset:         280
        .size:           8
        .value_kind:     hidden_global_offset_y
      - .offset:         288
        .size:           8
        .value_kind:     hidden_global_offset_z
      - .offset:         296
        .size:           2
        .value_kind:     hidden_grid_dims
      - .offset:         352
        .size:           4
        .value_kind:     hidden_dynamic_lds_size
    .group_segment_fixed_size: 0
    .kernarg_segment_align: 8
    .kernarg_segment_size: 488
    .language:       OpenCL C
    .language_version:
      - 2
      - 0
    .max_flat_workgroup_size: 512
    .name:           _Z9trunk_fwd4Args
    .private_segment_fixed_size: 0
    .sgpr_count:     108
    .sgpr_spill_count: 130
    .symbol:         _Z9trunk_fwd4Args.kd
    .uniform_work_group_size: 1
    .uses_dynamic_stack: false
    .vgpr_count:     256
    .vgpr_spill_count: 0
    .wavefront_size: 64
